# prep_rows (phase 0) row sum-of-squares wave reduction via DPP / permlane swaps instead of six ds_bpermute hops per row
# speedup vs baseline: 1.0043x; 1.0039x over previous
; __device__ __forceinline__ int tid_opq() { int t = threadIdx.x; asm volatile("" : "+v"(t)); return t; }
; __device__ __forceinline__ int bid_opq() { int b = blockIdx.x; asm volatile("" : "+s"(b)); return b; }
; __device__ __forceinline__ unsigned cvtpk(float lo, float hi) { f32x2_t v = {lo, hi}; bf16x2_t b = __builtin_convertvector(v, bf16x2_t); return __builtin_bit_cast(unsigned, b); }
; __device__ __forceinline__ float wave_sum(float v) { v += __shfl_xor(v, 32); v += __shfl_xor(v, 16); v += __shfl_xor(v, 8); v += __shfl_xor(v, 4); v += __shfl_xor(v, 2); v += __shfl_xor(v, 1); return v; }
; __device__ void prep_rows(const float* __restrict__ X, bf16_t* __restrict__ XB, float* __restrict__ PS, int rows) {
;     const int lane = tid_opq() & 63, gw = bid_opq() * 8 + (tid_opq() >> 6), stride = gridDim.x * 8;
;     for (int r = gw; r < rows; r += stride) {
;         const f32x4* xr = (const f32x4*)(X + (size_t)r * DM); float ss = 0.f;
; #pragma unroll
;         for (int i = 0; i < 4; ++i) { const f32x4 v = xr[lane + 64 * i]; ss += v[0] * v[0] + v[1] * v[1] + v[2] * v[2] + v[3] * v[3];
;             u32x2 w; w.x = cvtpk(v[0], v[1]); w.y = cvtpk(v[2], v[3]); *(u32x2*)(XB + (size_t)r * DM + (lane + 64 * i) * 4) = w; }
;         ss = wave_sum(ss);
;         if (lane == 0) PS[r] = ss;
;     }
; }
.LBB0_661:
	s_waitcnt lgkmcnt(0)
	global_load_dwordx4 v[14:17], v[6:7], off offset:-3072
	global_load_dwordx4 v[18:21], v[6:7], off offset:-2048
	global_load_dwordx4 v[22:25], v[6:7], off offset:-1024
	global_load_dwordx4 v[26:29], v[6:7], off
	s_waitcnt vmcnt(3)
	v_mul_f32_e32 v30, v15, v15
	s_waitcnt vmcnt(2)
	v_mul_f32_e32 v31, v19, v19
	s_waitcnt vmcnt(1)
	v_mul_f32_e32 v32, v23, v23
	v_fmac_f32_e32 v30, v14, v14
	v_fmac_f32_e32 v31, v18, v18
	s_waitcnt vmcnt(0)
	v_mul_f32_e32 v33, v27, v27
	v_fmac_f32_e32 v32, v22, v22
	v_fmac_f32_e32 v30, v16, v16
	v_fmac_f32_e32 v31, v20, v20
	v_fmac_f32_e32 v33, v26, v26
	v_fmac_f32_e32 v32, v24, v24
	v_fmac_f32_e32 v30, v17, v17
	v_fmac_f32_e32 v31, v21, v21
	v_fmac_f32_e32 v33, v28, v28
	v_fmac_f32_e32 v32, v25, v25
	v_add_f32_e32 v30, v30, v31
	v_add_f32_e32 v30, v30, v32
	v_fmac_f32_e32 v33, v29, v29
	v_add_f32_e32 v30, v30, v33
	v_mov_b32_e32 v60, v30
	v_mov_b32_e32 v31, v30
	s_nop 1
	v_permlane32_swap_b32_e32 v60, v31
	s_nop 1
	v_permlane32_swap_b32_e32 v31, v60
	s_nop 0
	v_cvt_pk_bf16_f32 v14, v14, v15
	v_cvt_pk_bf16_f32 v15, v16, v17
	global_store_dwordx2 v[4:5], v[14:15], off offset:-1024
	v_cvt_pk_bf16_f32 v14, v18, v19
	s_waitcnt lgkmcnt(0)
	v_add_f32_e32 v30, v30, v31
	v_mov_b32_e32 v60, v30
	v_mov_b32_e32 v31, v30
	s_nop 1
	v_permlane16_swap_b32_e32 v60, v31
	s_nop 1
	v_permlane16_swap_b32_e32 v31, v60
	s_nop 0
	v_cvt_pk_bf16_f32 v15, v20, v21
	global_store_dwordx2 v[4:5], v[14:15], off offset:-512
	v_cvt_pk_bf16_f32 v16, v22, v23
	v_cvt_pk_bf16_f32 v17, v24, v25
	s_waitcnt lgkmcnt(0)
	v_add_f32_e32 v30, v30, v31
	s_nop 1
	v_mov_b32_dpp v31, v30 row_ror:8 row_mask:0xf bank_mask:0xf
	global_store_dwordx2 v[4:5], v[16:17], off
	v_cvt_pk_bf16_f32 v16, v26, v27
	v_cvt_pk_bf16_f32 v17, v28, v29
	global_store_dwordx2 v[4:5], v[16:17], off offset:512
	s_waitcnt lgkmcnt(0)
	v_add_f32_e32 v30, v30, v31
	s_nop 1
	v_mov_b32_dpp v61, v30 quad_perm:[3,2,1,0] row_mask:0xf bank_mask:0xf
	s_nop 1
	v_mov_b32_dpp v31, v61 row_half_mirror row_mask:0xf bank_mask:0xf
	s_waitcnt lgkmcnt(0)
	v_add_f32_e32 v18, v30, v31
	s_nop 1
	v_mov_b32_dpp v19, v18 quad_perm:[2,3,0,1] row_mask:0xf bank_mask:0xf
	s_waitcnt lgkmcnt(0)
	v_add_f32_e32 v14, v18, v19
	s_nop 1
	v_mov_b32_dpp v15, v14 quad_perm:[1,0,3,2] row_mask:0xf bank_mask:0xf
	s_and_saveexec_b64 s[0:1], vcc
	s_cbranch_execz .LBB0_660
	s_waitcnt lgkmcnt(0)
	v_add_f32_e32 v14, v14, v15
	global_store_dword v[2:3], v14, off
	s_branch .LBB0_660
